# MLA: interleaved row-max phase, S written straight to VGPRs by QK MFMAs; both attention loops preload all K fragments at the loop head
# speedup vs baseline: 1.0797x; 1.0059x over previous
; DI f4 mfma16(h8 a, h8 b, f4 c) { return __builtin_amdgcn_mfma_f32_16x16x32_f16(a, b, c, 0, 0, 0); }
; template <int DQK, bool BIAS>
; __device__ __forceinline__ void attn_pass(const hf* __restrict__ Q, int ldq, const hf* __restrict__ Kp, int ldk, const hf* __restrict__ VT,
;                                           int s0, int L, int q0, float scale_l2, const float* sBias, f4 (&oacc)[8][4], char* smem) {
;     ...
; #pragma unroll
;     for (int mk = 0; mk < 4; ++mk) {
;       h8 kf[NKS];
; #pragma unroll
;       for (int ks = 0; ks < NKS; ++ks) kf[ks] = *(const h8*)(sK + (mk * 16 + fr) * KS + ks * 32 + (fq ^ (((fr >> 2) ^ (fr >> 3)) & 1)) * 8);
; #pragma unroll
;       for (int nq = 0; nq < 4; ++nq) {
;         f4 a = {0.f, 0.f, 0.f, 0.f};
; #pragma unroll
;         for (int ks = 0; ks < NKS; ++ks) a = mfma16(kf[ks], qf[nq][ks], a);
;         sacc[mk][nq] = a;
;       }
;     }
;     if (kt + 1 < nkt) storeKV((kt + 1) & 1);
.LBB0_1948:
	s_bitcmp1_b32 s16, 0
	s_cselect_b32 s17, 0x7c00, 0
	s_add_i32 s95, s17, 16
	v_add_u32_e32 v40, s95, v239
	v_lshl_add_u32 v36, v238, 1, v40
	v_add_u32_e32 v44, v40, v240
	ds_read_b128 v[32:35], v36
	ds_read_b128 v[36:39], v36 offset:64
	ds_read_b128 v[48:51], v44 offset:2304
	ds_read_b128 v[52:55], v44 offset:2368
	ds_read_b128 v[56:59], v44 offset:4608
	ds_read_b128 v[60:63], v44 offset:4672
	ds_read_b128 v[40:43], v44 offset:6912
	ds_read_b128 v[64:67], v44 offset:6976
	s_add_i32 s94, s16, 1
	s_waitcnt lgkmcnt(7)
	v_mfma_f32_16x16x32_f16 v[188:191], v[32:35], v[0:3], 0
	s_waitcnt lgkmcnt(6)
	v_mfma_f32_16x16x32_f16 v[188:191], v[36:39], v[4:7], v[188:191]
	v_mfma_f32_16x16x32_f16 v[156:159], v[32:35], v[16:19], 0
	v_mfma_f32_16x16x32_f16 v[172:175], v[32:35], v[8:11], 0
	v_mfma_f32_16x16x32_f16 v[156:159], v[36:39], v[20:23], v[156:159]
	v_mfma_f32_16x16x32_f16 v[124:127], v[32:35], v[24:27], 0
	v_mfma_f32_16x16x32_f16 v[172:175], v[36:39], v[12:15], v[172:175]
	v_mfma_f32_16x16x32_f16 v[124:127], v[36:39], v[28:31], v[124:127]
	s_waitcnt lgkmcnt(5)
	v_mfma_f32_16x16x32_f16 v[184:187], v[48:51], v[0:3], 0
	s_waitcnt lgkmcnt(4)
	v_mfma_f32_16x16x32_f16 v[184:187], v[52:55], v[4:7], v[184:187]
	v_mfma_f32_16x16x32_f16 v[168:171], v[48:51], v[8:11], 0
	v_mfma_f32_16x16x32_f16 v[168:171], v[52:55], v[12:15], v[168:171]
	v_mfma_f32_16x16x32_f16 v[152:155], v[48:51], v[16:19], 0
	v_mfma_f32_16x16x32_f16 v[152:155], v[52:55], v[20:23], v[152:155]
	v_mfma_f32_16x16x32_f16 v[120:123], v[48:51], v[24:27], 0
	v_mfma_f32_16x16x32_f16 v[120:123], v[52:55], v[28:31], v[120:123]
	s_waitcnt lgkmcnt(3)
	v_mfma_f32_16x16x32_f16 v[180:183], v[56:59], v[0:3], 0
	s_waitcnt lgkmcnt(2)
	v_mfma_f32_16x16x32_f16 v[180:183], v[60:63], v[4:7], v[180:183]
	v_mfma_f32_16x16x32_f16 v[164:167], v[56:59], v[8:11], 0
	v_mfma_f32_16x16x32_f16 v[164:167], v[60:63], v[12:15], v[164:167]
	v_mfma_f32_16x16x32_f16 v[148:151], v[56:59], v[16:19], 0
	v_mfma_f32_16x16x32_f16 v[148:151], v[60:63], v[20:23], v[148:151]
	v_mfma_f32_16x16x32_f16 v[116:119], v[56:59], v[24:27], 0
	s_waitcnt lgkmcnt(1)
	v_mfma_f32_16x16x32_f16 v[176:179], v[40:43], v[0:3], 0
	s_waitcnt lgkmcnt(0)
	v_mfma_f32_16x16x32_f16 v[176:179], v[64:67], v[4:7], v[176:179]
	v_mfma_f32_16x16x32_f16 v[160:163], v[40:43], v[8:11], 0
	v_mfma_f32_16x16x32_f16 v[160:163], v[64:67], v[12:15], v[160:163]
	v_mfma_f32_16x16x32_f16 v[144:147], v[40:43], v[16:19], 0
	v_mfma_f32_16x16x32_f16 v[144:147], v[64:67], v[20:23], v[144:147]
	v_mfma_f32_16x16x32_f16 v[112:115], v[40:43], v[24:27], 0
	v_mfma_f32_16x16x32_f16 v[116:119], v[60:63], v[28:31], v[116:119]
	v_mfma_f32_16x16x32_f16 v[112:115], v[64:67], v[28:31], v[112:115]
	s_cmp_ge_u32 s94, s73
	s_cbranch_scc1 .LBB0_1950
	s_bitcmp1_b32 s94, 0
	s_cselect_b32 s17, 0x7c00, 0
	s_add_i32 s17, s17, 16
	v_add3_u32 v32, s17, v211, v244
	s_waitcnt vmcnt(1)
	ds_write_b128 v32, a[200:203]
	s_waitcnt vmcnt(0)
	ds_write_b128 v32, a[204:207] offset:64
	v_add3_u32 v32, s17, v232, v210
	ds_write_b128 v32, a[192:195] offset:13312
	v_add3_u32 v32, s17, v234, v210
	ds_write_b128 v32, a[196:199] offset:13312
	v_add3_u32 v32, s17, v235, v210
	ds_write_b128 v32, a[208:211] offset:13312
	v_add3_u32 v32, s17, v236, v210
	ds_write_b128 v32, a[212:215] offset:13312

; DI f4 mfma16(h8 a, h8 b, f4 c) { return __builtin_amdgcn_mfma_f32_16x16x32_f16(a, b, c, 0, 0, 0); }
; template <int DQK, bool BIAS>
; __device__ __forceinline__ void attn_pass(const hf* __restrict__ Q, int ldq, const hf* __restrict__ Kp, int ldk, const hf* __restrict__ VT,
;                                           int s0, int L, int q0, float scale_l2, const float* sBias, f4 (&oacc)[8][4], char* smem) {
;     ...
; #pragma unroll
;     for (int mk = 0; mk < 4; ++mk) {
;       h8 kf[NKS];
; #pragma unroll
;       for (int ks = 0; ks < NKS; ++ks) kf[ks] = *(const h8*)(sK + (mk * 16 + fr) * KS + ks * 32 + (fq ^ (((fr >> 2) ^ (fr >> 3)) & 1)) * 8);
; #pragma unroll
;       for (int nq = 0; nq < 4; ++nq) {
;         f4 a = {0.f, 0.f, 0.f, 0.f};
; #pragma unroll
;         for (int ks = 0; ks < NKS; ++ks) a = mfma16(kf[ks], qf[nq][ks], a);
;         sacc[mk][nq] = a;
;       }
;     }
;     if (kt + 1 < nkt) storeKV((kt + 1) & 1);
.LBB0_1994:
	s_bitcmp1_b32 s19, 0
	s_cselect_b32 s14, 0x7c00, 0
	s_add_i32 s15, s14, 16
	v_add3_u32 v64, s15, v208, v233
	ds_read_b128 v[48:51], v64
	ds_read_b128 v[52:55], v64 offset:64
	ds_read_b128 v[56:59], v64 offset:128
	ds_read_b128 v[60:63], v64 offset:3328
	ds_read_b128 v[88:91], v64 offset:3392
	ds_read_b128 v[92:95], v64 offset:3456
	ds_read_b128 v[96:99], v64 offset:6656
	ds_read_b128 v[100:103], v64 offset:6720
	ds_read_b128 v[108:111], v64 offset:6784
	ds_read_b128 v[112:115], v64 offset:9984
	ds_read_b128 v[116:119], v64 offset:10048
	ds_read_b128 v[120:123], v64 offset:10112
	s_add_i32 s14, s19, 1
	s_waitcnt lgkmcnt(11)
	v_mfma_f32_16x16x32_f16 v[68:71], v[48:51], v[0:3], 0
	s_waitcnt lgkmcnt(10)
	v_mfma_f32_16x16x32_f16 v[68:71], v[52:55], v[4:7], v[68:71]
	s_waitcnt lgkmcnt(9)
	v_mfma_f32_16x16x32_f16 v[68:71], v[56:59], v[8:11], v[68:71]
	v_mfma_f32_16x16x32_f16 v[172:175], v[48:51], v[24:27], 0
	v_mfma_f32_16x16x32_f16 v[172:175], v[52:55], v[28:31], v[172:175]
	v_mfma_f32_16x16x32_f16 v[80:83], v[48:51], v[12:15], 0
	v_mfma_f32_16x16x32_f16 v[172:175], v[56:59], v[32:35], v[172:175]
	v_mfma_f32_16x16x32_f16 v[124:127], v[48:51], v[36:39], 0
	v_mfma_f32_16x16x32_f16 v[80:83], v[52:55], v[16:19], v[80:83]
	v_mfma_f32_16x16x32_f16 v[124:127], v[52:55], v[40:43], v[124:127]
	v_mfma_f32_16x16x32_f16 v[80:83], v[56:59], v[20:23], v[80:83]
	s_waitcnt lgkmcnt(8)
	v_mfma_f32_16x16x32_f16 v[204:207], v[60:63], v[0:3], 0
	s_waitcnt lgkmcnt(7)
	v_mfma_f32_16x16x32_f16 v[204:207], v[88:91], v[4:7], v[204:207]
	s_waitcnt lgkmcnt(6)
	v_mfma_f32_16x16x32_f16 v[204:207], v[92:95], v[8:11], v[204:207]
	v_mfma_f32_16x16x32_f16 v[72:75], v[60:63], v[12:15], 0
	v_mfma_f32_16x16x32_f16 v[72:75], v[88:91], v[16:19], v[72:75]
	v_mfma_f32_16x16x32_f16 v[72:75], v[92:95], v[20:23], v[72:75]
	v_mfma_f32_16x16x32_f16 v[168:171], v[60:63], v[24:27], 0
	v_mfma_f32_16x16x32_f16 v[168:171], v[88:91], v[28:31], v[168:171]
	v_mfma_f32_16x16x32_f16 v[168:171], v[92:95], v[32:35], v[168:171]
	v_mfma_f32_16x16x32_f16 v[104:107], v[60:63], v[36:39], 0
	v_mfma_f32_16x16x32_f16 v[104:107], v[88:91], v[40:43], v[104:107]
	v_mfma_f32_16x16x32_f16 v[104:107], v[92:95], v[44:47], v[104:107]
	s_waitcnt lgkmcnt(5)
	v_mfma_f32_16x16x32_f16 v[200:203], v[96:99], v[0:3], 0
	v_mfma_f32_16x16x32_f16 v[124:127], v[56:59], v[44:47], v[124:127]
	s_waitcnt lgkmcnt(4)
	v_mfma_f32_16x16x32_f16 v[200:203], v[100:103], v[4:7], v[200:203]
	s_waitcnt lgkmcnt(3)
	v_mfma_f32_16x16x32_f16 v[200:203], v[108:111], v[8:11], v[200:203]
	v_mfma_f32_16x16x32_f16 v[188:191], v[96:99], v[12:15], 0
	v_mfma_f32_16x16x32_f16 v[188:191], v[100:103], v[16:19], v[188:191]
	v_mfma_f32_16x16x32_f16 v[188:191], v[108:111], v[20:23], v[188:191]
	v_mfma_f32_16x16x32_f16 v[164:167], v[96:99], v[24:27], 0
	v_mfma_f32_16x16x32_f16 v[164:167], v[100:103], v[28:31], v[164:167]
	v_mfma_f32_16x16x32_f16 v[164:167], v[108:111], v[32:35], v[164:167]
	v_mfma_f32_16x16x32_f16 v[84:87], v[96:99], v[36:39], 0
	v_mfma_f32_16x16x32_f16 v[84:87], v[100:103], v[40:43], v[84:87]
	s_waitcnt lgkmcnt(2)
	v_mfma_f32_16x16x32_f16 v[196:199], v[112:115], v[0:3], 0
	s_waitcnt lgkmcnt(1)
	v_mfma_f32_16x16x32_f16 v[196:199], v[116:119], v[4:7], v[196:199]
	s_waitcnt lgkmcnt(0)
	v_mfma_f32_16x16x32_f16 v[196:199], v[120:123], v[8:11], v[196:199]
	v_mfma_f32_16x16x32_f16 v[184:187], v[112:115], v[12:15], 0
	v_mfma_f32_16x16x32_f16 v[184:187], v[116:119], v[16:19], v[184:187]
	v_mfma_f32_16x16x32_f16 v[184:187], v[120:123], v[20:23], v[184:187]
	v_mfma_f32_16x16x32_f16 v[160:163], v[112:115], v[24:27], 0
	v_mfma_f32_16x16x32_f16 v[160:163], v[116:119], v[28:31], v[160:163]
	v_mfma_f32_16x16x32_f16 v[160:163], v[120:123], v[32:35], v[160:163]
	v_mfma_f32_16x16x32_f16 v[76:79], v[112:115], v[36:39], 0
	v_mfma_f32_16x16x32_f16 v[76:79], v[116:119], v[40:43], v[76:79]
	v_mfma_f32_16x16x32_f16 v[84:87], v[108:111], v[44:47], v[84:87]
	v_mfma_f32_16x16x32_f16 v[76:79], v[120:123], v[44:47], v[76:79]
	s_cmp_ge_u32 s14, s18
	s_cbranch_scc1 .LBB0_1996
	s_bitcmp1_b32 s14, 0
	s_cselect_b32 s27, 0x7c00, 0
	s_add_i32 s27, s27, 16
	v_add3_u32 v48, s27, v213, v238
	s_waitcnt vmcnt(6)
	ds_write_b128 v48, v[246:249]
	s_waitcnt vmcnt(1)
	ds_write_b128 v48, a[196:199] offset:64
	s_waitcnt vmcnt(0)
	ds_write_b128 v48, a[204:207] offset:128
	v_add3_u32 v48, s27, v229, v212
	ds_write_b128 v48, v[250:253] offset:13312
	v_add3_u32 v48, s27, v230, v212
	ds_write_b128 v48, a[192:195] offset:13312
	v_add3_u32 v48, s27, v231, v212
	ds_write_b128 v48, a[200:203] offset:13312
	v_add3_u32 v48, s27, v232, v212
	ds_write_b128 v48, a[208:211] offset:13312

; DI float max3_(float a, float b, float c) { float r; asm("v_max3_f32 %0, %1, %2, %3" : "=v"(r) : "v"(a), "v"(b), "v"(c)); return r; }
; template <int DQK, bool BIAS>
; __device__ __forceinline__ void attn_pass(const hf* __restrict__ Q, int ldq, const hf* __restrict__ Kp, int ldk, const hf* __restrict__ VT,
;                                           int s0, int L, int q0, float scale_l2, const float* sBias, f4 (&oacc)[8][4], char* smem) {
;     ...
;       float mx = -1e30f;
; #pragma unroll
;       for (int mk = 0; mk < 4; ++mk) { mx = max3_(mx, sacc[mk][nq][0], sacc[mk][nq][1]); mx = max3_(mx, sacc[mk][nq][2], sacc[mk][nq][3]); }
;       mx = max3_(mx, shx(mx, 16), mx); mx = max3_(mx, shx(mx, 32), mx);
;       if (!BIAS) mx *= scale_l2;
;       const bool upd = mx > mrun[nq] + 8.f;
;       const float mnew = upd ? mx : mrun[nq];
;       if (__builtin_amdgcn_ballot_w64(upd) != 0) {
;         const float alpha = __builtin_amdgcn_exp2f(mrun[nq] - mnew);
;         lrun[nq] *= alpha;
; #pragma unroll
;         for (int md = 0; md < 8; ++md) { oacc[md][nq][0] *= alpha; oacc[md][nq][1] *= alpha; oacc[md][nq][2] *= alpha; oacc[md][nq][3] *= alpha; }
;       }
;       mrun[nq] = mnew;
.LBB0_1998:
	s_nop 7
	v_max3_f32 v88, v226, v68, v69
	v_max3_f32 v89, v226, v80, v81
	v_max3_f32 v90, v226, v172, v173
	v_max3_f32 v91, v226, v124, v125
	v_max3_f32 v88, v88, v70, v71
	v_max3_f32 v89, v89, v82, v83
	v_max3_f32 v90, v90, v174, v175
	v_max3_f32 v91, v91, v126, v127
	v_max3_f32 v88, v88, v204, v205
	v_max3_f32 v89, v89, v72, v73
	v_max3_f32 v90, v90, v168, v169
	v_max3_f32 v91, v91, v104, v105
	v_max3_f32 v88, v88, v206, v207
	v_max3_f32 v89, v89, v74, v75
	v_max3_f32 v90, v90, v170, v171
	v_max3_f32 v91, v91, v106, v107
	v_max3_f32 v88, v88, v200, v201
	v_max3_f32 v89, v89, v188, v189
	v_max3_f32 v90, v90, v164, v165
	v_max3_f32 v91, v91, v84, v85
	v_max3_f32 v88, v88, v202, v203
	v_max3_f32 v89, v89, v190, v191
	v_max3_f32 v90, v90, v166, v167
	v_max3_f32 v91, v91, v86, v87
	v_max3_f32 v88, v88, v196, v197
	v_max3_f32 v89, v89, v184, v185
	v_max3_f32 v90, v90, v160, v161
	v_max3_f32 v91, v91, v76, v77
	v_max3_f32 v88, v88, v198, v199
	v_max3_f32 v89, v89, v186, v187
	v_max3_f32 v90, v90, v162, v163
	v_max3_f32 v91, v91, v78, v79
	v_mov_b32_e32 v92, v88
	v_mov_b32_e32 v93, v89
	v_mov_b32_e32 v94, v90
	v_mov_b32_e32 v95, v91
	v_permlane16_swap_b32_e32 v92, v88
	v_permlane16_swap_b32_e32 v93, v89
	v_permlane16_swap_b32_e32 v94, v90
	v_permlane16_swap_b32_e32 v95, v91
	v_max_f32_e32 v88, v88, v92
	v_max_f32_e32 v89, v89, v93
	v_max_f32_e32 v90, v90, v94
	v_max_f32_e32 v91, v91, v95
	v_mov_b32_e32 v92, v88
	v_mov_b32_e32 v93, v89
	v_mov_b32_e32 v94, v90
	v_mov_b32_e32 v95, v91
	v_permlane32_swap_b32_e32 v92, v88
	v_permlane32_swap_b32_e32 v93, v89
	v_permlane32_swap_b32_e32 v94, v90
	v_permlane32_swap_b32_e32 v95, v91
	v_max_f32_e32 v88, v88, v92
	v_max_f32_e32 v89, v89, v93
	v_max_f32_e32 v90, v90, v94
	v_max_f32_e32 v91, v91, v95
	v_mul_f32_e32 v88, 0x3e16c740, v88
	v_mul_f32_e32 v89, 0x3e16c740, v89
	v_mul_f32_e32 v90, 0x3e16c740, v90
	v_mul_f32_e32 v91, 0x3e16c740, v91
	v_add_f32_e32 v92, 0x41000000, v225
	v_add_f32_e32 v93, 0x41000000, v244
	v_add_f32_e32 v94, 0x41000000, v243
	v_add_f32_e32 v95, 0x41000000, v242
	v_cmp_gt_f32_e32 vcc, v88, v92
	v_cmp_gt_f32_e64 s[38:39], v89, v93
	s_nop 0
	v_cndmask_b32_e32 v241, v225, v88, vcc
	v_cndmask_b32_e64 v192, v244, v89, s[38:39]
	v_cmp_gt_f32_e32 vcc, v90, v94
	v_cmp_gt_f32_e64 s[38:39], v91, v95
	s_nop 0
	v_cndmask_b32_e32 v176, v243, v90, vcc
	v_cndmask_b32_e64 v128, v242, v91, s[38:39]
	v_sub_f32_e32 v96, v241, v225
	v_sub_f32_e32 v97, v192, v244
	v_sub_f32_e32 v98, v176, v243
	v_sub_f32_e32 v99, v128, v242
	v_add_f32_e32 v96, v96, v97
	v_add_f32_e32 v98, v98, v99
	v_add_f32_e32 v96, v96, v98
	v_cmp_lg_f32_e32 vcc, 0, v96
	s_nop 1
	s_cbranch_vccz .LBB0_2006
	v_cmp_lg_f32_e32 vcc, v241, v225
	s_nop 3
	s_cbranch_vccz .Lmla_slow_0
	v_sub_f32_e32 v129, v225, v241
	v_exp_f32_e32 v130, v129
	s_nop 0
	v_accvgpr_read_b32 v88, a92
	v_accvgpr_read_b32 v89, a108
	v_accvgpr_read_b32 v90, a76
	v_accvgpr_read_b32 v91, a64
	v_accvgpr_read_b32 v92, a40
	v_accvgpr_read_b32 v93, a28
	v_accvgpr_read_b32 v94, a8
	v_accvgpr_read_b32 v95, a0
	v_accvgpr_read_b32 v96, a109
	v_accvgpr_read_b32 v97, a110
	v_accvgpr_read_b32 v98, a111
	v_accvgpr_read_b32 v99, a93
	v_accvgpr_read_b32 v100, a94
	v_accvgpr_read_b32 v101, a95
	v_accvgpr_read_b32 v102, a77
	v_accvgpr_read_b32 v103, a78
	v_accvgpr_read_b32 v108, a79
	v_accvgpr_read_b32 v109, a65
	v_accvgpr_read_b32 v110, a66
	v_accvgpr_read_b32 v111, a67
	v_accvgpr_read_b32 v112, a41
	v_accvgpr_read_b32 v113, a42
	v_accvgpr_read_b32 v114, a43
	v_accvgpr_read_b32 v115, a29
	v_accvgpr_read_b32 v116, a30
	v_accvgpr_read_b32 v117, a31
	v_accvgpr_read_b32 v118, a9
	v_accvgpr_read_b32 v119, a10
	v_accvgpr_read_b32 v120, a11
	v_accvgpr_read_b32 v121, a1
	v_accvgpr_read_b32 v122, a2
	v_accvgpr_read_b32 v123, a3
	v_pk_mul_f32 v[88:89], v[88:89], v[130:131] op_sel_hi:[1,0]
	v_pk_mul_f32 v[90:91], v[90:91], v[130:131] op_sel_hi:[1,0]
	v_pk_mul_f32 v[92:93], v[92:93], v[130:131] op_sel_hi:[1,0]
	v_pk_mul_f32 v[94:95], v[94:95], v[130:131] op_sel_hi:[1,0]
	v_pk_mul_f32 v[96:97], v[96:97], v[130:131] op_sel_hi:[1,0]
	v_pk_mul_f32 v[98:99], v[98:99], v[130:131] op_sel_hi:[1,0]
	v_pk_mul_f32 v[100:101], v[100:101], v[130:131] op_sel_hi:[1,0]
	v_pk_mul_f32 v[102:103], v[102:103], v[130:131] op_sel_hi:[1,0]
	v_pk_mul_f32 v[108:109], v[108:109], v[130:131] op_sel_hi:[1,0]
	v_pk_mul_f32 v[110:111], v[110:111], v[130:131] op_sel_hi:[1,0]
	v_pk_mul_f32 v[112:113], v[112:113], v[130:131] op_sel_hi:[1,0]
	v_pk_mul_f32 v[114:115], v[114:115], v[130:131] op_sel_hi:[1,0]
	v_pk_mul_f32 v[116:117], v[116:117], v[130:131] op_sel_hi:[1,0]
	v_pk_mul_f32 v[118:119], v[118:119], v[130:131] op_sel_hi:[1,0]
	v_pk_mul_f32 v[120:121], v[120:121], v[130:131] op_sel_hi:[1,0]
	v_pk_mul_f32 v[122:123], v[122:123], v[130:131] op_sel_hi:[1,0]
	v_mul_f32_e32 v240, v240, v130
	v_accvgpr_write_b32 a92, v88
	v_accvgpr_write_b32 a108, v89
	v_accvgpr_write_b32 a76, v90
	v_accvgpr_write_b32 a64, v91
	v_accvgpr_write_b32 a40, v92
	v_accvgpr_write_b32 a28, v93
	v_accvgpr_write_b32 a8, v94
	v_accvgpr_write_b32 a0, v95
	v_accvgpr_write_b32 a109, v96
	v_accvgpr_write_b32 a110, v97
	v_accvgpr_write_b32 a111, v98
	v_accvgpr_write_b32 a93, v99
	v_accvgpr_write_b32 a94, v100
	v_accvgpr_write_b32 a95, v101
	v_accvgpr_write_b32 a77, v102
	v_accvgpr_write_b32 a78, v103
	v_accvgpr_write_b32 a79, v108
	v_accvgpr_write_b32 a65, v109
	v_accvgpr_write_b32 a66, v110
	v_accvgpr_write_b32 a67, v111
	v_accvgpr_write_b32 a41, v112
	v_accvgpr_write_b32 a42, v113
	v_accvgpr_write_b32 a43, v114
	v_accvgpr_write_b32 a29, v115
	v_accvgpr_write_b32 a30, v116
	v_accvgpr_write_b32 a31, v117
	v_accvgpr_write_b32 a9, v118
	v_accvgpr_write_b32 a10, v119
	v_accvgpr_write_b32 a11, v120
	v_accvgpr_write_b32 a1, v121
	v_accvgpr_write_b32 a2, v122
	v_accvgpr_write_b32 a3, v123
; template <int DQK, bool BIAS>
; __device__ __forceinline__ void attn_pass(const hf* __restrict__ Q, int ldq, const hf* __restrict__ Kp, int ldk, const hf* __restrict__ VT,
;                                           int s0, int L, int q0, float scale_l2, const float* sBias, f4 (&oacc)[8][4], char* smem) {
;     ...
;       const bool upd = mx > mrun[nq] + 8.f;
;       const float mnew = upd ? mx : mrun[nq];
;       if (__builtin_amdgcn_ballot_w64(upd) != 0) {
;         const float alpha = __builtin_amdgcn_exp2f(mrun[nq] - mnew);
;         lrun[nq] *= alpha;
; #pragma unroll
;         for (int md = 0; md < 8; ++md) { oacc[md][nq][0] *= alpha; oacc[md][nq][1] *= alpha; oacc[md][nq][2] *= alpha; oacc[md][nq][3] *= alpha; }
;       }
;       mrun[nq] = mnew;
.Lmla_slow_0:
	v_cmp_lg_f32_e32 vcc, v192, v244
	s_nop 3
	s_cbranch_vccz .Lmla_slow_1
	v_sub_f32_e32 v129, v244, v192
	v_exp_f32_e32 v130, v129
	s_nop 0
	v_accvgpr_read_b32 v88, a103
	v_accvgpr_read_b32 v89, a119
	v_accvgpr_read_b32 v90, a84
	v_accvgpr_read_b32 v91, a68
	v_accvgpr_read_b32 v92, a48
	v_accvgpr_read_b32 v93, a32
	v_accvgpr_read_b32 v94, a16
	v_accvgpr_read_b32 v95, a4
	v_accvgpr_read_b32 v96, a118
	v_accvgpr_read_b32 v97, a117
	v_accvgpr_read_b32 v98, a116
	v_accvgpr_read_b32 v99, a102
	v_accvgpr_read_b32 v100, a101
	v_accvgpr_read_b32 v101, a100
	v_accvgpr_read_b32 v102, a85
	v_accvgpr_read_b32 v103, a86
	v_accvgpr_read_b32 v108, a87
	v_accvgpr_read_b32 v109, a69
	v_accvgpr_read_b32 v110, a70
	v_accvgpr_read_b32 v111, a71
	v_accvgpr_read_b32 v112, a49
	v_accvgpr_read_b32 v113, a50
	v_accvgpr_read_b32 v114, a51
	v_accvgpr_read_b32 v115, a33
	v_accvgpr_read_b32 v116, a34
	v_accvgpr_read_b32 v117, a35
	v_accvgpr_read_b32 v118, a17
	v_accvgpr_read_b32 v119, a18
	v_accvgpr_read_b32 v120, a19
	v_accvgpr_read_b32 v121, a5
	v_accvgpr_read_b32 v122, a6
	v_accvgpr_read_b32 v123, a7
	v_pk_mul_f32 v[88:89], v[88:89], v[130:131] op_sel_hi:[1,0]
	v_pk_mul_f32 v[90:91], v[90:91], v[130:131] op_sel_hi:[1,0]
	v_pk_mul_f32 v[92:93], v[92:93], v[130:131] op_sel_hi:[1,0]
	v_pk_mul_f32 v[94:95], v[94:95], v[130:131] op_sel_hi:[1,0]
	v_pk_mul_f32 v[96:97], v[96:97], v[130:131] op_sel_hi:[1,0]
	v_pk_mul_f32 v[98:99], v[98:99], v[130:131] op_sel_hi:[1,0]
	v_pk_mul_f32 v[100:101], v[100:101], v[130:131] op_sel_hi:[1,0]
	v_pk_mul_f32 v[102:103], v[102:103], v[130:131] op_sel_hi:[1,0]
	v_pk_mul_f32 v[108:109], v[108:109], v[130:131] op_sel_hi:[1,0]
	v_pk_mul_f32 v[110:111], v[110:111], v[130:131] op_sel_hi:[1,0]
	v_pk_mul_f32 v[112:113], v[112:113], v[130:131] op_sel_hi:[1,0]
	v_pk_mul_f32 v[114:115], v[114:115], v[130:131] op_sel_hi:[1,0]
	v_pk_mul_f32 v[116:117], v[116:117], v[130:131] op_sel_hi:[1,0]
	v_pk_mul_f32 v[118:119], v[118:119], v[130:131] op_sel_hi:[1,0]
	v_pk_mul_f32 v[120:121], v[120:121], v[130:131] op_sel_hi:[1,0]
	v_pk_mul_f32 v[122:123], v[122:123], v[130:131] op_sel_hi:[1,0]
	v_mul_f32_e32 v237, v237, v130
	v_accvgpr_write_b32 a103, v88
	v_accvgpr_write_b32 a119, v89
	v_accvgpr_write_b32 a84, v90
	v_accvgpr_write_b32 a68, v91
	v_accvgpr_write_b32 a48, v92
	v_accvgpr_write_b32 a32, v93
	v_accvgpr_write_b32 a16, v94
	v_accvgpr_write_b32 a4, v95
	v_accvgpr_write_b32 a118, v96
	v_accvgpr_write_b32 a117, v97
	v_accvgpr_write_b32 a116, v98
	v_accvgpr_write_b32 a102, v99
	v_accvgpr_write_b32 a101, v100
	v_accvgpr_write_b32 a100, v101
	v_accvgpr_write_b32 a85, v102
	v_accvgpr_write_b32 a86, v103
	v_accvgpr_write_b32 a87, v108
	v_accvgpr_write_b32 a69, v109
	v_accvgpr_write_b32 a70, v110
	v_accvgpr_write_b32 a71, v111
	v_accvgpr_write_b32 a49, v112
	v_accvgpr_write_b32 a50, v113
	v_accvgpr_write_b32 a51, v114
	v_accvgpr_write_b32 a33, v115
	v_accvgpr_write_b32 a34, v116
	v_accvgpr_write_b32 a35, v117
	v_accvgpr_write_b32 a17, v118
	v_accvgpr_write_b32 a18, v119
	v_accvgpr_write_b32 a19, v120
	v_accvgpr_write_b32 a5, v121
	v_accvgpr_write_b32 a6, v122
	v_accvgpr_write_b32 a7, v123
.Lmla_slow_1:
	v_cmp_lg_f32_e32 vcc, v176, v243
	s_nop 3
	s_cbranch_vccz .Lmla_slow_2
	v_sub_f32_e32 v129, v243, v176
	v_exp_f32_e32 v130, v129
	s_nop 0
	v_accvgpr_read_b32 v88, a104
	v_accvgpr_read_b32 v89, a120
	v_accvgpr_read_b32 v90, a88
	v_accvgpr_read_b32 v91, a72
	v_accvgpr_read_b32 v92, a56
	v_accvgpr_read_b32 v93, a44
	v_accvgpr_read_b32 v94, a24
	v_accvgpr_read_b32 v95, a12
	v_accvgpr_read_b32 v96, a121
	v_accvgpr_read_b32 v97, a122
	v_accvgpr_read_b32 v98, a123
	v_accvgpr_read_b32 v99, a105
	v_accvgpr_read_b32 v100, a106
	v_accvgpr_read_b32 v101, a107
	v_accvgpr_read_b32 v102, a89
	v_accvgpr_read_b32 v103, a90
	v_accvgpr_read_b32 v108, a91
	v_accvgpr_read_b32 v109, a73
	v_accvgpr_read_b32 v110, a74
	v_accvgpr_read_b32 v111, a75
	v_accvgpr_read_b32 v112, a57
	v_accvgpr_read_b32 v113, a58
	v_accvgpr_read_b32 v114, a59
	v_accvgpr_read_b32 v115, a45
	v_accvgpr_read_b32 v116, a46
	v_accvgpr_read_b32 v117, a47
	v_accvgpr_read_b32 v118, a25
	v_accvgpr_read_b32 v119, a26
	v_accvgpr_read_b32 v120, a27
	v_accvgpr_read_b32 v121, a13
	v_accvgpr_read_b32 v122, a14
	v_accvgpr_read_b32 v123, a15
	v_pk_mul_f32 v[88:89], v[88:89], v[130:131] op_sel_hi:[1,0]
	v_pk_mul_f32 v[90:91], v[90:91], v[130:131] op_sel_hi:[1,0]
	v_pk_mul_f32 v[92:93], v[92:93], v[130:131] op_sel_hi:[1,0]
	v_pk_mul_f32 v[94:95], v[94:95], v[130:131] op_sel_hi:[1,0]
	v_pk_mul_f32 v[96:97], v[96:97], v[130:131] op_sel_hi:[1,0]
	v_pk_mul_f32 v[98:99], v[98:99], v[130:131] op_sel_hi:[1,0]
	v_pk_mul_f32 v[100:101], v[100:101], v[130:131] op_sel_hi:[1,0]
	v_pk_mul_f32 v[102:103], v[102:103], v[130:131] op_sel_hi:[1,0]
	v_pk_mul_f32 v[108:109], v[108:109], v[130:131] op_sel_hi:[1,0]
	v_pk_mul_f32 v[110:111], v[110:111], v[130:131] op_sel_hi:[1,0]
	v_pk_mul_f32 v[112:113], v[112:113], v[130:131] op_sel_hi:[1,0]
	v_pk_mul_f32 v[114:115], v[114:115], v[130:131] op_sel_hi:[1,0]
	v_pk_mul_f32 v[116:117], v[116:117], v[130:131] op_sel_hi:[1,0]
	v_pk_mul_f32 v[118:119], v[118:119], v[130:131] op_sel_hi:[1,0]
	v_pk_mul_f32 v[120:121], v[120:121], v[130:131] op_sel_hi:[1,0]
	v_pk_mul_f32 v[122:123], v[122:123], v[130:131] op_sel_hi:[1,0]
	v_mul_f32_e32 v236, v236, v130
	v_accvgpr_write_b32 a104, v88
	v_accvgpr_write_b32 a120, v89
	v_accvgpr_write_b32 a88, v90
	v_accvgpr_write_b32 a72, v91
	v_accvgpr_write_b32 a56, v92
	v_accvgpr_write_b32 a44, v93
	v_accvgpr_write_b32 a24, v94
	v_accvgpr_write_b32 a12, v95
	v_accvgpr_write_b32 a121, v96
	v_accvgpr_write_b32 a122, v97
	v_accvgpr_write_b32 a123, v98
	v_accvgpr_write_b32 a105, v99
	v_accvgpr_write_b32 a106, v100
	v_accvgpr_write_b32 a107, v101
	v_accvgpr_write_b32 a89, v102
	v_accvgpr_write_b32 a90, v103
	v_accvgpr_write_b32 a91, v108
	v_accvgpr_write_b32 a73, v109
	v_accvgpr_write_b32 a74, v110
	v_accvgpr_write_b32 a75, v111
	v_accvgpr_write_b32 a57, v112
	v_accvgpr_write_b32 a58, v113
	v_accvgpr_write_b32 a59, v114
	v_accvgpr_write_b32 a45, v115
	v_accvgpr_write_b32 a46, v116
	v_accvgpr_write_b32 a47, v117
	v_accvgpr_write_b32 a25, v118
	v_accvgpr_write_b32 a26, v119
	v_accvgpr_write_b32 a27, v120
	v_accvgpr_write_b32 a13, v121
	v_accvgpr_write_b32 a14, v122
	v_accvgpr_write_b32 a15, v123
; template <int DQK, bool BIAS>
; __device__ __forceinline__ void attn_pass(const hf* __restrict__ Q, int ldq, const hf* __restrict__ Kp, int ldk, const hf* __restrict__ VT,
;                                           int s0, int L, int q0, float scale_l2, const float* sBias, f4 (&oacc)[8][4], char* smem) {
;     ...
;       const bool upd = mx > mrun[nq] + 8.f;
;       const float mnew = upd ? mx : mrun[nq];
;       if (__builtin_amdgcn_ballot_w64(upd) != 0) {
;         const float alpha = __builtin_amdgcn_exp2f(mrun[nq] - mnew);
;         lrun[nq] *= alpha;
; #pragma unroll
;         for (int md = 0; md < 8; ++md) { oacc[md][nq][0] *= alpha; oacc[md][nq][1] *= alpha; oacc[md][nq][2] *= alpha; oacc[md][nq][3] *= alpha; }
;       }
;       mrun[nq] = mnew;
;       float ps = 0.f;
; #pragma unroll
;       for (int mk = 0; mk < 4; ++mk)
; #pragma unroll
;         for (int j = 0; j < 4; ++j) {
;           float pe = BIAS ? __builtin_amdgcn_exp2f(sacc[mk][nq][j] - mnew) : __builtin_amdgcn_exp2f(sacc[mk][nq][j] * scale_l2 - mnew);
;           sacc[mk][nq][j] = pe; ps += pe;
;         }
.Lmla_slow_2:
	v_cmp_lg_f32_e32 vcc, v128, v242
	s_nop 3
	s_cbranch_vccz .Lmla_slow_3
	v_sub_f32_e32 v129, v242, v128
	v_exp_f32_e32 v130, v129
	s_nop 0
	v_accvgpr_read_b32 v88, a115
	v_accvgpr_read_b32 v89, a127
	v_accvgpr_read_b32 v90, a96
	v_accvgpr_read_b32 v91, a80
	v_accvgpr_read_b32 v92, a60
	v_accvgpr_read_b32 v93, a52
	v_accvgpr_read_b32 v94, a36
	v_accvgpr_read_b32 v95, a20
	v_accvgpr_read_b32 v96, a126
	v_accvgpr_read_b32 v97, a125
	v_accvgpr_read_b32 v98, a124
	v_accvgpr_read_b32 v99, a114
	v_accvgpr_read_b32 v100, a113
	v_accvgpr_read_b32 v101, a112
	v_accvgpr_read_b32 v102, a97
	v_accvgpr_read_b32 v103, a98
	v_accvgpr_read_b32 v108, a99
	v_accvgpr_read_b32 v109, a81
	v_accvgpr_read_b32 v110, a82
	v_accvgpr_read_b32 v111, a83
	v_accvgpr_read_b32 v112, a61
	v_accvgpr_read_b32 v113, a62
	v_accvgpr_read_b32 v114, a63
	v_accvgpr_read_b32 v115, a53
	v_accvgpr_read_b32 v116, a54
	v_accvgpr_read_b32 v117, a55
	v_accvgpr_read_b32 v118, a37
	v_accvgpr_read_b32 v119, a38
	v_accvgpr_read_b32 v120, a39
	v_accvgpr_read_b32 v121, a21
	v_accvgpr_read_b32 v122, a22
	v_accvgpr_read_b32 v123, a23
	v_pk_mul_f32 v[88:89], v[88:89], v[130:131] op_sel_hi:[1,0]
	v_pk_mul_f32 v[90:91], v[90:91], v[130:131] op_sel_hi:[1,0]
	v_pk_mul_f32 v[92:93], v[92:93], v[130:131] op_sel_hi:[1,0]
	v_pk_mul_f32 v[94:95], v[94:95], v[130:131] op_sel_hi:[1,0]
	v_pk_mul_f32 v[96:97], v[96:97], v[130:131] op_sel_hi:[1,0]
	v_pk_mul_f32 v[98:99], v[98:99], v[130:131] op_sel_hi:[1,0]
	v_pk_mul_f32 v[100:101], v[100:101], v[130:131] op_sel_hi:[1,0]
	v_pk_mul_f32 v[102:103], v[102:103], v[130:131] op_sel_hi:[1,0]
	v_pk_mul_f32 v[108:109], v[108:109], v[130:131] op_sel_hi:[1,0]
	v_pk_mul_f32 v[110:111], v[110:111], v[130:131] op_sel_hi:[1,0]
	v_pk_mul_f32 v[112:113], v[112:113], v[130:131] op_sel_hi:[1,0]
	v_pk_mul_f32 v[114:115], v[114:115], v[130:131] op_sel_hi:[1,0]
	v_pk_mul_f32 v[116:117], v[116:117], v[130:131] op_sel_hi:[1,0]
	v_pk_mul_f32 v[118:119], v[118:119], v[130:131] op_sel_hi:[1,0]
	v_pk_mul_f32 v[120:121], v[120:121], v[130:131] op_sel_hi:[1,0]
	v_pk_mul_f32 v[122:123], v[122:123], v[130:131] op_sel_hi:[1,0]
	v_mul_f32_e32 v235, v235, v130
	v_accvgpr_write_b32 a115, v88
	v_accvgpr_write_b32 a127, v89
	v_accvgpr_write_b32 a96, v90
	v_accvgpr_write_b32 a80, v91
	v_accvgpr_write_b32 a60, v92
	v_accvgpr_write_b32 a52, v93
	v_accvgpr_write_b32 a36, v94
	v_accvgpr_write_b32 a20, v95
	v_accvgpr_write_b32 a126, v96
	v_accvgpr_write_b32 a125, v97
	v_accvgpr_write_b32 a124, v98
	v_accvgpr_write_b32 a114, v99
	v_accvgpr_write_b32 a113, v100
	v_accvgpr_write_b32 a112, v101
	v_accvgpr_write_b32 a97, v102
	v_accvgpr_write_b32 a98, v103
	v_accvgpr_write_b32 a99, v108
	v_accvgpr_write_b32 a81, v109
	v_accvgpr_write_b32 a82, v110
	v_accvgpr_write_b32 a83, v111
	v_accvgpr_write_b32 a61, v112
	v_accvgpr_write_b32 a62, v113
	v_accvgpr_write_b32 a63, v114
	v_accvgpr_write_b32 a53, v115
	v_accvgpr_write_b32 a54, v116
	v_accvgpr_write_b32 a55, v117
	v_accvgpr_write_b32 a37, v118
	v_accvgpr_write_b32 a38, v119
	v_accvgpr_write_b32 a39, v120
	v_accvgpr_write_b32 a21, v121
	v_accvgpr_write_b32 a22, v122
	v_accvgpr_write_b32 a23, v123
.Lmla_slow_3:
.LBB0_2006:
	v_fma_f32 v52, v188, s26, -v192
	v_exp_f32_e32 v112, v52
	v_fma_f32 v52, v189, s26, -v192
	v_exp_f32_e32 v113, v52
	v_fma_f32 v52, v190, s26, -v192
	v_exp_f32_e32 v114, v52
	v_fma_f32 v52, v68, s26, -v241
	v_exp_f32_e32 v115, v52
	v_fma_f32 v52, v69, s26, -v241
	v_exp_f32_e32 v116, v52
	v_fma_f32 v52, v70, s26, -v241
	v_exp_f32_e32 v117, v52
	v_fma_f32 v52, v71, s26, -v241
	v_exp_f32_e32 v118, v52
	v_fma_f32 v52, v204, s26, -v241
	v_fma_f32 v72, v72, s26, -v192
	v_exp_f32_e32 v119, v52
	v_fma_f32 v52, v205, s26, -v241
	v_exp_f32_e32 v108, v72
	v_fma_f32 v72, v73, s26, -v192
	v_exp_f32_e32 v120, v52
	v_fma_f32 v52, v206, s26, -v241
	v_exp_f32_e32 v109, v72
	v_fma_f32 v72, v74, s26, -v192
	v_exp_f32_e32 v121, v52
	v_fma_f32 v52, v207, s26, -v241
	v_exp_f32_e32 v110, v72
	v_fma_f32 v72, v75, s26, -v192
	v_exp_f32_e32 v122, v52
	v_fma_f32 v52, v200, s26, -v241
	v_exp_f32_e32 v111, v72
	v_exp_f32_e32 v123, v52
	v_fma_f32 v52, v201, s26, -v241
	v_fma_f32 v72, v124, s26, -v128
	v_exp_f32_e32 v129, v52
	v_fma_f32 v52, v202, s26, -v241
	v_exp_f32_e32 v124, v72
	v_fma_f32 v72, v125, s26, -v128
	v_exp_f32_e32 v130, v52
	v_fma_f32 v52, v203, s26, -v241
	v_exp_f32_e32 v125, v72
	v_fma_f32 v72, v126, s26, -v128
	v_exp_f32_e32 v131, v52
	v_fma_f32 v52, v196, s26, -v241
	v_exp_f32_e32 v126, v72
	v_fma_f32 v72, v127, s26, -v128
	v_exp_f32_e32 v132, v52
	v_fma_f32 v52, v197, s26, -v241
	v_exp_f32_e32 v127, v72
	v_fma_f32 v72, v104, s26, -v128
	v_exp_f32_e32 v133, v52
	v_fma_f32 v52, v198, s26, -v241
	v_exp_f32_e32 v104, v72
	v_fma_f32 v72, v105, s26, -v128
	v_exp_f32_e32 v134, v52
	v_fma_f32 v52, v199, s26, -v241
	v_add3_u32 v136, s15, v234, v239
	v_exp_f32_e32 v105, v72
	v_fma_f32 v72, v106, s26, -v128
	v_exp_f32_e32 v135, v52
	v_add_u32_e32 v52, 0x3000, v136
	v_exp_f32_e32 v106, v72
	v_fma_f32 v72, v107, s26, -v128
	ds_read2_b64 v[146:149], v52 offset0:128 offset1:132
	ds_read2_b64 v[150:153], v52 offset0:136 offset1:140
	v_add_u32_e32 v52, 0x3800, v136
	v_exp_f32_e32 v107, v72
	v_fma_f32 v72, v84, s26, -v128
	ds_read2_b64 v[154:157], v52 offset0:160 offset1:164
	v_add_u32_e32 v53, 0x4000, v136
	v_exp_f32_e32 v84, v72
	v_fma_f32 v72, v85, s26, -v128
	v_fma_f32 v96, v164, s26, -v176
	v_fma_f32 v97, v165, s26, -v176
	v_fma_f32 v102, v162, s26, -v176
	v_fma_f32 v103, v163, s26, -v176
	ds_read2_b64 v[162:165], v53 offset0:192 offset1:196
	v_exp_f32_e32 v85, v72
	v_fma_f32 v72, v86, s26, -v128
	v_fma_f32 v88, v172, s26, -v176
	v_fma_f32 v89, v173, s26, -v176
; DI f4 mfma16(h8 a, h8 b, f4 c) { return __builtin_amdgcn_mfma_f32_16x16x32_f16(a, b, c, 0, 0, 0); }
; template <int DQK, bool BIAS>
; __device__ __forceinline__ void attn_pass(const hf* __restrict__ Q, int ldq, const hf* __restrict__ Kp, int ldk, const hf* __restrict__ VT,
;                                           int s0, int L, int q0, float scale_l2, const float* sBias, f4 (&oacc)[8][4], char* smem) {
;     ...
;       float ps = 0.f;
; #pragma unroll
;       for (int mk = 0; mk < 4; ++mk)
; #pragma unroll
;         for (int j = 0; j < 4; ++j) {
;           float pe = BIAS ? __builtin_amdgcn_exp2f(sacc[mk][nq][j] - mnew) : __builtin_amdgcn_exp2f(sacc[mk][nq][j] * scale_l2 - mnew);
;           sacc[mk][nq][j] = pe; ps += pe;
;         }
;       lrun[nq] += ps;
; #pragma unroll
;       for (int s2 = 0; s2 < 2; ++s2)
; #pragma unroll
;         for (int i = 0; i < 8; ++i) pf[nq][s2][i] = (hf)sacc[2 * s2 + (i >> 2)][nq][i & 3];
;     }
; #pragma unroll
;     for (int mh = 0; mh < 2; ++mh) {
;       h8 vf[4][2];
; #pragma unroll
;       for (int m4 = 0; m4 < 4; ++m4)
; #pragma unroll
;         for (int s2 = 0; s2 < 2; ++s2) {
;           h4 v0 = *(const h4*)(sVT + ((mh * 4 + m4) * 16 + fr) * 72 + s2 * 32 + fq * 4);
;           h4 v1 = *(const h4*)(sVT + ((mh * 4 + m4) * 16 + fr) * 72 + s2 * 32 + 16 + fq * 4);
;           vf[m4][s2] = __builtin_shufflevector(v0, v1, 0, 1, 2, 3, 4, 5, 6, 7);
;         }
; #pragma unroll
;       for (int nq = 0; nq < 4; ++nq)
; #pragma unroll
;         for (int m4 = 0; m4 < 4; ++m4) {
;           oacc[mh * 4 + m4][nq] = mfma16(vf[m4][0], pf[nq][0], oacc[mh * 4 + m4][nq]);
;           oacc[mh * 4 + m4][nq] = mfma16(vf[m4][1], pf[nq][1], oacc[mh * 4 + m4][nq]);
;         }
	v_fma_f32 v90, v174, s26, -v176
	v_fma_f32 v91, v175, s26, -v176
	v_fma_f32 v92, v168, s26, -v176
	v_fma_f32 v93, v169, s26, -v176
	v_fma_f32 v94, v170, s26, -v176
	v_fma_f32 v95, v171, s26, -v176
	v_fma_f32 v80, v80, s26, -v192
	v_fma_f32 v81, v81, s26, -v192
	v_fma_f32 v82, v82, s26, -v192
	v_fma_f32 v83, v83, s26, -v192
	v_exp_f32_e32 v86, v72
	v_fma_f32 v72, v87, s26, -v128
	v_exp_f32_e32 v88, v88
	v_exp_f32_e32 v89, v89
	v_exp_f32_e32 v90, v90
	v_exp_f32_e32 v91, v91
	v_exp_f32_e32 v92, v92
	v_exp_f32_e32 v93, v93
	v_exp_f32_e32 v94, v94
	v_exp_f32_e32 v95, v95
	v_exp_f32_e32 v80, v80
	v_exp_f32_e32 v81, v81
	v_exp_f32_e32 v82, v82
	v_exp_f32_e32 v83, v83
	v_fma_f32 v48, v184, s26, -v192
	v_exp_f32_e32 v87, v72
	v_fma_f32 v72, v76, s26, -v128
	v_fma_f32 v100, v160, s26, -v176
	v_fma_f32 v101, v161, s26, -v176
	ds_read2_b64 v[158:161], v52 offset0:168 offset1:172
	v_exp_f32_e32 v138, v48
	v_add_u32_e32 v48, 0x4800, v136
	v_exp_f32_e32 v142, v72
	v_fma_f32 v72, v77, s26, -v128
	v_fma_f32 v98, v166, s26, -v176
	v_fma_f32 v99, v167, s26, -v176
	ds_read2_b64 v[166:169], v53 offset0:200 offset1:204
	ds_read2_b64 v[170:173], v48 offset0:224 offset1:228
	ds_read2_b64 v[178:181], v48 offset0:232 offset1:236
	v_fma_f32 v48, v186, s26, -v192
	v_exp_f32_e32 v143, v72
	v_fma_f32 v72, v78, s26, -v128
	v_fma_f32 v52, v191, s26, -v192
	v_fma_f32 v49, v185, s26, -v192
	v_exp_f32_e32 v140, v48
	v_fma_f32 v48, v187, s26, -v192
	v_exp_f32_e32 v144, v72
	v_fma_f32 v72, v79, s26, -v128
	v_exp_f32_e32 v96, v96
	v_exp_f32_e32 v97, v97
	v_exp_f32_e32 v98, v98
	v_exp_f32_e32 v99, v99
	v_exp_f32_e32 v100, v100
	v_exp_f32_e32 v101, v101
	v_exp_f32_e32 v102, v102
	v_exp_f32_e32 v103, v103
	v_cvt_pk_f16_f32 v59, v121, v122
	v_cvt_pk_f16_f32 v58, v119, v120
	v_cvt_pk_f16_f32 v57, v117, v118
	v_cvt_pk_f16_f32 v56, v115, v116
	v_exp_f32_e32 v137, v52
	v_exp_f32_e32 v139, v49
	v_exp_f32_e32 v141, v48
	v_cvt_pk_f16_f32 v51, v110, v111
	v_cvt_pk_f16_f32 v50, v108, v109
	v_cvt_pk_f16_f32 v49, v82, v83
	v_cvt_pk_f16_f32 v48, v80, v81
	v_cvt_pk_f16_f32 v67, v94, v95
	v_cvt_pk_f16_f32 v66, v92, v93
	v_cvt_pk_f16_f32 v65, v90, v91
	v_cvt_pk_f16_f32 v64, v88, v89
	v_exp_f32_e32 v145, v72
	v_cvt_pk_f16_f32 v75, v106, v107
	v_cvt_pk_f16_f32 v74, v104, v105
	v_cvt_pk_f16_f32 v73, v126, v127
	v_cvt_pk_f16_f32 v72, v124, v125
	s_waitcnt lgkmcnt(7)
	v_mfma_f32_16x16x32_f16 a[0:3], v[146:149], v[56:59], a[0:3]
	v_cvt_pk_f16_f32 v63, v134, v135
	v_cvt_pk_f16_f32 v62, v132, v133
	v_cvt_pk_f16_f32 v61, v130, v131
	v_mfma_f32_16x16x32_f16 a[4:7], v[146:149], v[48:51], a[4:7]
	v_cvt_pk_f16_f32 v60, v123, v129
	v_cvt_pk_f16_f32 v55, v140, v141
	v_cvt_pk_f16_f32 v54, v138, v139
	v_mfma_f32_16x16x32_f16 a[12:15], v[146:149], v[64:67], a[12:15]
	v_cvt_pk_f16_f32 v53, v114, v137
	v_cvt_pk_f16_f32 v52, v112, v113
	v_cvt_pk_f16_f32 v71, v102, v103
	v_mfma_f32_16x16x32_f16 a[20:23], v[146:149], v[72:75], a[20:23]
	v_cvt_pk_f16_f32 v70, v100, v101
	v_cvt_pk_f16_f32 v69, v98, v99
	v_cvt_pk_f16_f32 v68, v96, v97
	s_waitcnt lgkmcnt(5)
	v_mfma_f32_16x16x32_f16 a[8:11], v[154:157], v[56:59], a[8:11]
	v_cvt_pk_f16_f32 v79, v144, v145
	v_cvt_pk_f16_f32 v78, v142, v143
	v_cvt_pk_f16_f32 v77, v86, v87
	v_mfma_f32_16x16x32_f16 a[16:19], v[154:157], v[48:51], a[16:19]
	v_cvt_pk_f16_f32 v76, v84, v85
	v_add_u32_e32 v146, 0x5800, v136
	s_add_i32 s12, s12, 64
	v_mfma_f32_16x16x32_f16 a[24:27], v[154:157], v[64:67], a[24:27]
	s_cmp_lg_u32 s18, s14
	v_mfma_f32_16x16x32_f16 a[36:39], v[154:157], v[72:75], a[36:39]
	s_waitcnt lgkmcnt(4)
	v_mfma_f32_16x16x32_f16 a[28:31], v[162:165], v[56:59], a[28:31]
	v_mfma_f32_16x16x32_f16 a[32:35], v[162:165], v[48:51], a[32:35]
	v_mfma_f32_16x16x32_f16 a[44:47], v[162:165], v[64:67], a[44:47]
	v_mfma_f32_16x16x32_f16 a[52:55], v[162:165], v[72:75], a[52:55]
	v_mfma_f32_16x16x32_f16 a[0:3], v[150:153], v[60:63], a[0:3]
	v_mfma_f32_16x16x32_f16 a[4:7], v[150:153], v[52:55], a[4:7]
	v_mfma_f32_16x16x32_f16 a[12:15], v[150:153], v[68:71], a[12:15]
	v_mfma_f32_16x16x32_f16 a[20:23], v[150:153], v[76:79], a[20:23]
	ds_read2_b64 v[148:151], v146 offset1:4
	ds_read2_b64 v[152:155], v146 offset0:8 offset1:12
	v_add_u32_e32 v146, 0x6000, v136
	s_waitcnt lgkmcnt(5)
	v_mfma_f32_16x16x32_f16 a[8:11], v[158:161], v[60:63], a[8:11]
	v_mfma_f32_16x16x32_f16 a[16:19], v[158:161], v[52:55], a[16:19]
	v_mfma_f32_16x16x32_f16 a[24:27], v[158:161], v[68:71], a[24:27]
	v_mfma_f32_16x16x32_f16 a[36:39], v[158:161], v[76:79], a[36:39]
	ds_read2_b64 v[156:159], v146 offset0:32 offset1:36
	ds_read2_b64 v[160:163], v146 offset0:40 offset1:44
	v_add_u32_e32 v146, 0x6800, v136
	v_add_u32_e32 v136, 0x7000, v136
	s_waitcnt lgkmcnt(6)
	v_mfma_f32_16x16x32_f16 a[28:31], v[166:169], v[60:63], a[28:31]
	s_waitcnt lgkmcnt(5)
	v_mfma_f32_16x16x32_f16 a[40:43], v[170:173], v[56:59], a[40:43]
	v_mfma_f32_16x16x32_f16 a[32:35], v[166:169], v[52:55], a[32:35]
	v_mfma_f32_16x16x32_f16 a[48:51], v[170:173], v[48:51], a[48:51]
	v_mfma_f32_16x16x32_f16 a[44:47], v[166:169], v[68:71], a[44:47]
	v_mfma_f32_16x16x32_f16 a[56:59], v[170:173], v[64:67], a[56:59]
	v_mfma_f32_16x16x32_f16 a[52:55], v[166:169], v[76:79], a[52:55]
	ds_read2_b64 v[164:167], v146 offset0:64 offset1:68
	v_mfma_f32_16x16x32_f16 a[60:63], v[170:173], v[72:75], a[60:63]
	ds_read2_b64 v[172:175], v136 offset0:96 offset1:100
	ds_read2_b64 v[168:171], v146 offset0:72 offset1:76
	s_waitcnt lgkmcnt(6)
; DI f4 mfma16(h8 a, h8 b, f4 c) { return __builtin_amdgcn_mfma_f32_16x16x32_f16(a, b, c, 0, 0, 0); }
; template <int DQK, bool BIAS>
; __device__ __forceinline__ void attn_pass(const hf* __restrict__ Q, int ldq, const hf* __restrict__ Kp, int ldk, const hf* __restrict__ VT,
;                                           int s0, int L, int q0, float scale_l2, const float* sBias, f4 (&oacc)[8][4], char* smem) {
;     ...
;       float ps = 0.f;
; #pragma unroll
;       for (int mk = 0; mk < 4; ++mk)
; #pragma unroll
;         for (int j = 0; j < 4; ++j) {
;           float pe = BIAS ? __builtin_amdgcn_exp2f(sacc[mk][nq][j] - mnew) : __builtin_amdgcn_exp2f(sacc[mk][nq][j] * scale_l2 - mnew);
;           sacc[mk][nq][j] = pe; ps += pe;
;         }
;       lrun[nq] += ps;
; #pragma unroll
;       for (int s2 = 0; s2 < 2; ++s2)
; #pragma unroll
;         for (int i = 0; i < 8; ++i) pf[nq][s2][i] = (hf)sacc[2 * s2 + (i >> 2)][nq][i & 3];
;     }
; #pragma unroll
;     for (int mh = 0; mh < 2; ++mh) {
;       h8 vf[4][2];
; #pragma unroll
;       for (int m4 = 0; m4 < 4; ++m4)
; #pragma unroll
;         for (int s2 = 0; s2 < 2; ++s2) {
;           h4 v0 = *(const h4*)(sVT + ((mh * 4 + m4) * 16 + fr) * 72 + s2 * 32 + fq * 4);
;           h4 v1 = *(const h4*)(sVT + ((mh * 4 + m4) * 16 + fr) * 72 + s2 * 32 + 16 + fq * 4);
;           vf[m4][s2] = __builtin_shufflevector(v0, v1, 0, 1, 2, 3, 4, 5, 6, 7);
;         }
; #pragma unroll
;       for (int nq = 0; nq < 4; ++nq)
; #pragma unroll
;         for (int m4 = 0; m4 < 4; ++m4) {
;           oacc[mh * 4 + m4][nq] = mfma16(vf[m4][0], pf[nq][0], oacc[mh * 4 + m4][nq]);
;           oacc[mh * 4 + m4][nq] = mfma16(vf[m4][1], pf[nq][1], oacc[mh * 4 + m4][nq]);
;         }
;     }
;     __syncthreads();
	v_mfma_f32_16x16x32_f16 a[68:71], v[148:151], v[48:51], a[68:71]
	s_waitcnt lgkmcnt(4)
	v_mfma_f32_16x16x32_f16 a[84:87], v[156:159], v[48:51], a[84:87]
	s_waitcnt lgkmcnt(2)
	v_mfma_f32_16x16x32_f16 a[100:103], v[164:167], v[48:51], a[100:103]
	s_waitcnt lgkmcnt(1)
	v_mfma_f32_16x16x32_f16 a[116:119], v[172:175], v[48:51], a[116:119]
	v_add_f32_e32 v48, 0, v80
	v_add_f32_e32 v48, v81, v48
	v_add_f32_e32 v48, v82, v48
	v_add_f32_e32 v48, v83, v48
	v_add_f32_e32 v48, v108, v48
	v_add_f32_e32 v48, v109, v48
	v_add_f32_e32 v48, v110, v48
	v_add_f32_e32 v48, v111, v48
	v_add_f32_e32 v48, v112, v48
	v_add_f32_e32 v48, v113, v48
	v_add_f32_e32 v48, v114, v48
	v_add_f32_e32 v48, v137, v48
	v_add_f32_e32 v48, v138, v48
	v_add_f32_e32 v48, v139, v48
	v_add_f32_e32 v48, v140, v48
	v_add_f32_e32 v48, v141, v48
	v_add_f32_e32 v237, v48, v237
	v_add_f32_e32 v48, 0, v115
	v_add_f32_e32 v48, v116, v48
	v_add_f32_e32 v48, v117, v48
	v_add_f32_e32 v48, v118, v48
	v_add_f32_e32 v48, v119, v48
	v_add_f32_e32 v48, v120, v48
	v_add_f32_e32 v48, v121, v48
	v_add_f32_e32 v48, v122, v48
	v_add_f32_e32 v48, v123, v48
	v_add_f32_e32 v48, v129, v48
	v_add_f32_e32 v48, v130, v48
	v_add_f32_e32 v48, v131, v48
	v_add_f32_e32 v48, v132, v48
	v_add_f32_e32 v48, v133, v48
	v_add_f32_e32 v48, v134, v48
	v_add_f32_e32 v48, v135, v48
	v_mfma_f32_16x16x32_f16 a[64:67], v[148:151], v[56:59], a[64:67]
	v_add_f32_e32 v240, v48, v240
	v_add_f32_e32 v48, 0, v124
	v_add_f32_e32 v48, v125, v48
	v_mfma_f32_16x16x32_f16 a[76:79], v[156:159], v[56:59], a[76:79]
	v_add_f32_e32 v48, v126, v48
	v_add_f32_e32 v48, v127, v48
	v_add_f32_e32 v48, v104, v48
	v_mfma_f32_16x16x32_f16 a[92:95], v[164:167], v[56:59], a[92:95]
	v_add_f32_e32 v48, v105, v48
	v_add_f32_e32 v48, v106, v48
	v_add_f32_e32 v48, v107, v48
	v_mfma_f32_16x16x32_f16 a[108:111], v[172:175], v[56:59], a[108:111]
	v_add_f32_e32 v56, 0, v88
	v_add_f32_e32 v56, v89, v56
	v_add_f32_e32 v56, v90, v56
	v_add_f32_e32 v56, v91, v56
	v_mfma_f32_16x16x32_f16 a[40:43], v[178:181], v[60:63], a[40:43]
	v_add_f32_e32 v56, v92, v56
	v_add_f32_e32 v56, v93, v56
	v_add_f32_e32 v56, v94, v56
	v_mfma_f32_16x16x32_f16 a[48:51], v[178:181], v[52:55], a[48:51]
	v_add_f32_e32 v56, v95, v56
	v_add_f32_e32 v56, v96, v56
	v_add_f32_e32 v48, v84, v48
	v_mfma_f32_16x16x32_f16 a[56:59], v[178:181], v[68:71], a[56:59]
	v_add_f32_e32 v56, v97, v56
	v_add_f32_e32 v48, v85, v48
	v_add_f32_e32 v56, v98, v56
	v_mfma_f32_16x16x32_f16 a[60:63], v[178:181], v[76:79], a[60:63]
	ds_read2_b64 v[178:181], v136 offset0:104 offset1:108
	v_add_f32_e32 v48, v86, v48
	v_add_f32_e32 v56, v99, v56
	v_mfma_f32_16x16x32_f16 a[72:75], v[148:151], v[64:67], a[72:75]
	v_add_f32_e32 v48, v87, v48
	v_add_f32_e32 v56, v100, v56
	v_add_f32_e32 v48, v142, v48
	v_mfma_f32_16x16x32_f16 a[88:91], v[156:159], v[64:67], a[88:91]
	v_add_f32_e32 v56, v101, v56
	v_add_f32_e32 v48, v143, v48
	v_add_f32_e32 v56, v102, v56
	v_mfma_f32_16x16x32_f16 a[104:107], v[164:167], v[64:67], a[104:107]
	v_add_f32_e32 v48, v144, v48
	v_add_f32_e32 v56, v103, v56
	v_add_f32_e32 v48, v145, v48
	v_mfma_f32_16x16x32_f16 a[120:123], v[172:175], v[64:67], a[120:123]
	v_add_f32_e32 v236, v56, v236
	v_add_f32_e32 v235, v48, v235
	s_waitcnt lgkmcnt(0)
	v_mfma_f32_16x16x32_f16 a[80:83], v[148:151], v[72:75], a[80:83]
	s_barrier
	v_mfma_f32_16x16x32_f16 a[96:99], v[156:159], v[72:75], a[96:99]
	v_mfma_f32_16x16x32_f16 a[112:115], v[164:167], v[72:75], a[112:115]
	v_mfma_f32_16x16x32_f16 a[124:127], v[172:175], v[72:75], a[124:127]
	v_mfma_f32_16x16x32_f16 a[64:67], v[152:155], v[60:63], a[64:67]
	v_mfma_f32_16x16x32_f16 a[76:79], v[160:163], v[60:63], a[76:79]
	v_mfma_f32_16x16x32_f16 a[92:95], v[168:171], v[60:63], a[92:95]
	v_mfma_f32_16x16x32_f16 a[108:111], v[178:181], v[60:63], a[108:111]
	v_mfma_f32_16x16x32_f16 a[68:71], v[152:155], v[52:55], a[68:71]
	v_mfma_f32_16x16x32_f16 a[84:87], v[160:163], v[52:55], a[84:87]
	v_mfma_f32_16x16x32_f16 a[100:103], v[168:171], v[52:55], a[100:103]
	v_mfma_f32_16x16x32_f16 a[116:119], v[178:181], v[52:55], a[116:119]
	v_mfma_f32_16x16x32_f16 a[72:75], v[152:155], v[68:71], a[72:75]
	v_mfma_f32_16x16x32_f16 a[88:91], v[160:163], v[68:71], a[88:91]
	v_mfma_f32_16x16x32_f16 a[104:107], v[168:171], v[68:71], a[104:107]
	v_mfma_f32_16x16x32_f16 a[120:123], v[178:181], v[68:71], a[120:123]
	v_mfma_f32_16x16x32_f16 a[80:83], v[152:155], v[76:79], a[80:83]
	v_mfma_f32_16x16x32_f16 a[96:99], v[160:163], v[76:79], a[96:99]
	v_mfma_f32_16x16x32_f16 a[112:115], v[168:171], v[76:79], a[112:115]
	v_mfma_f32_16x16x32_f16 a[124:127], v[178:181], v[76:79], a[124:127]
	s_cbranch_scc0 .LBB0_1982
	v_mov_b32_e32 v242, v128
	v_mov_b32_e32 v243, v176
	v_mov_b32_e32 v244, v192
	v_mov_b32_e32 v225, v241
	s_mov_b32 s19, s14
	s_branch .LBB0_1994
